# FF2 sample tiles: the two sample workgroups of a panel on one XCD take the same K quarter of two column tiles (shared A slice)
# baseline (speedup 1.0000x reference)
.LBB0_411:
	s_or_b64 exec, exec, s[0:1]
	s_cmpk_lt_i32 s2, 0x330
	s_mul_hi_i32 s0, s2, 0xa0a0a0a1
	s_cselect_b64 s[26:27], -1, 0
	s_add_i32 s0, s0, s2
	s_lshr_b32 s1, s0, 31
	s_lshr_b32 s0, s0, 9
	s_add_i32 s0, s0, s1
	s_mulk_i32 s0, 0x330
	s_sub_i32 s0, s2, s0
	s_sext_i32_i16 s1, s0
	s_bfe_u32 s1, s1, 0x3001c
	s_add_i32 s1, s0, s1
	s_sext_i32_i16 s3, s1
	s_and_b32 s1, s1, 0xfff8
	s_ashr_i32 s6, s3, 3
	s_sub_i32 s8, s0, s1
	s_sub_i32 s80, s94, 48
	s_sub_i32 s0, s2, 48
	s_cmp_gt_u32 s2, 47
	s_cselect_b32 s81, s0, 0x10000000
	s_cmpk_lt_i32 s81, 0x198
	s_cselect_b64 s[0:1], -1, 0
	v_writelane_b32 v245, s0, 3
	s_waitcnt lgkmcnt(0)
	v_mov_b32_e32 v0, 0xe0
	v_sub_co_u32_e32 v0, vcc, s2, v0
	v_writelane_b32 v245, s1, 4
	s_mul_hi_i32 s0, s81, 0xa0a0a0a1
	s_add_i32 s0, s0, s81
	s_lshr_b32 s1, s0, 31
	s_lshr_b32 s0, s0, 8
	s_add_i32 s0, s0, s1
	s_mulk_i32 s0, 0x198
	s_sub_i32 s0, s81, s0
	s_sext_i32_i16 s1, s0
	s_bfe_u32 s1, s1, 0x3001c
	s_add_i32 s1, s0, s1
	s_sext_i32_i16 s3, s1
	s_and_b32 s1, s1, 0xfff8
	s_ashr_i32 s5, s3, 3
	s_sub_i32 s7, s0, s1
	s_cmpk_lt_i32 s2, 0x110
	s_cselect_b64 s[0:1], -1, 0
	v_writelane_b32 v245, s0, 5
	s_bfe_u32 s87, s2, 0x50002
	s_lshr_b32 s3, s2, 2
	v_writelane_b32 v245, s1, 6
	s_and_b32 s0, s2, 3
	s_lshl_b32 s89, s87, 6
	s_lshl_b32 s1, s0, 2
	s_lshl_b32 s0, s0, 8
	s_cmp_lg_u32 s87, 0
	v_writelane_b32 v245, s1, 7
	s_cselect_b64 s[36:37], -1, 0
	s_cmp_eq_u32 s87, 31
	v_writelane_b32 v245, s0, 8
	s_cselect_b64 s[38:39], -1, 0
	s_lshl_b32 s0, s2, 8
	s_and_b32 s0, s0, 0x300
	s_cmp_eq_u32 s87, 0
	v_writelane_b32 v245, s0, 9
	s_cselect_b64 s[0:1], -1, 0
	v_writelane_b32 v245, s0, 10
	s_cmp_gt_u32 s87, 1
	s_movk_i32 s93, 0x67
	v_writelane_b32 v245, s1, 11
	s_cselect_b64 s[0:1], -1, 0
	v_writelane_b32 v245, s0, 12
	s_cmp_gt_u32 s87, 2
	v_mov_b32_e32 v185, 0
	v_writelane_b32 v245, s1, 13
	s_cselect_b64 s[0:1], -1, 0
	v_writelane_b32 v245, s0, 14
	s_cmp_gt_u32 s87, 3
	v_mov_b32_e32 v216, 0x358637bd
	v_writelane_b32 v245, s1, 15
	s_cselect_b64 s[0:1], -1, 0
	v_writelane_b32 v245, s0, 16
	s_cmp_gt_u32 s87, 4
	v_mov_b32_e32 v217, 0x1000
	v_writelane_b32 v245, s1, 17
	s_cselect_b64 s[0:1], -1, 0
	v_writelane_b32 v245, s0, 18
	s_cmp_gt_u32 s87, 5
	v_mov_b32_e32 v218, 0x2000
	v_writelane_b32 v245, s1, 19
	s_cselect_b64 s[0:1], -1, 0
	v_writelane_b32 v245, s0, 20
	s_cmp_gt_u32 s87, 6
	v_mov_b32_e32 v219, 0x11083000
	v_writelane_b32 v245, s1, 21
	s_cselect_b64 s[0:1], -1, 0
	v_writelane_b32 v245, s0, 22
	s_cmp_gt_u32 s87, 7
	v_mov_b32_e32 v220, 1
	v_writelane_b32 v245, s1, 23
	s_cselect_b64 s[0:1], -1, 0
	v_writelane_b32 v245, s0, 24
	s_cmp_gt_u32 s87, 8
	v_mov_b32_e32 v222, 0x3000
	v_writelane_b32 v245, s1, 25
	s_cselect_b64 s[0:1], -1, 0
	s_cmp_gt_u32 s87, 9
	s_cselect_b64 s[40:41], -1, 0
	s_cmp_gt_u32 s87, 10
	s_cselect_b64 s[42:43], -1, 0
	s_cmp_gt_u32 s87, 11
	s_cselect_b64 s[44:45], -1, 0
	s_cmp_gt_u32 s87, 12
	s_cselect_b64 s[46:47], -1, 0
	s_cmp_gt_u32 s87, 13
	v_writelane_b32 v245, s0, 26
	s_cselect_b64 s[48:49], -1, 0
	s_cmp_gt_u32 s87, 14
	v_writelane_b32 v245, s1, 27
	s_cselect_b64 s[0:1], -1, 0
	v_writelane_b32 v245, s0, 28
	s_cmp_gt_u32 s87, 15
	v_mov_b32_e32 v223, 0x2200
	v_writelane_b32 v245, s1, 29
	s_cselect_b64 s[0:1], -1, 0
	v_writelane_b32 v245, s0, 30
	s_cmp_gt_u32 s87, 16
	s_movk_i32 s90, 0x4000
	v_writelane_b32 v245, s1, 31
	s_cselect_b64 s[0:1], -1, 0
	v_writelane_b32 v245, s0, 32
	s_cmp_gt_u32 s87, 17
	s_movk_i32 s68, 0x4800
	v_writelane_b32 v245, s1, 33
	s_cselect_b64 s[0:1], -1, 0
	v_writelane_b32 v245, s0, 34
	s_cmp_gt_u32 s87, 18
	s_mov_b32 s69, 0xffff0000
	v_writelane_b32 v245, s1, 35
	s_cselect_b64 s[0:1], -1, 0
	v_writelane_b32 v245, s0, 36
	s_cmp_gt_u32 s87, 19
	s_movk_i32 s50, 0x3000
	v_writelane_b32 v245, s1, 37
	s_cselect_b64 s[0:1], -1, 0
	v_writelane_b32 v245, s0, 38
	s_cmp_gt_u32 s87, 20
	s_mov_b32 s52, 0
	v_writelane_b32 v245, s1, 39
	s_cselect_b64 s[0:1], -1, 0
	v_writelane_b32 v245, s0, 40
	s_cmp_gt_u32 s87, 21
	s_mov_b32 s97, 0
	v_writelane_b32 v245, s1, 41
	s_cselect_b64 s[0:1], -1, 0
	v_writelane_b32 v245, s0, 42
	s_cmp_gt_u32 s87, 22
	s_nop 0
	v_writelane_b32 v245, s1, 43
	s_cselect_b64 s[0:1], -1, 0
	v_writelane_b32 v245, s0, 44
	s_cmp_gt_u32 s87, 23
	s_barrier
	v_writelane_b32 v245, s1, 45
	s_cselect_b64 s[0:1], -1, 0
	v_writelane_b32 v245, s0, 46
	s_cmp_gt_u32 s87, 24
	s_nop 0
	v_writelane_b32 v245, s1, 47
	s_cselect_b64 s[0:1], -1, 0
	v_writelane_b32 v245, s0, 48
	s_cmp_gt_u32 s87, 25
	s_nop 0
	v_writelane_b32 v245, s1, 49
	s_cselect_b64 s[0:1], -1, 0
	v_writelane_b32 v245, s0, 50
	s_cmp_gt_u32 s87, 26
	s_nop 0
	v_writelane_b32 v245, s1, 51
	s_cselect_b64 s[0:1], -1, 0
	v_writelane_b32 v245, s0, 52
	s_cmp_gt_u32 s87, 27
	s_nop 0
	v_writelane_b32 v245, s1, 53
	s_cselect_b64 s[0:1], -1, 0
	v_writelane_b32 v245, s0, 54
	s_cmp_gt_u32 s87, 28
	s_nop 0
	v_writelane_b32 v245, s1, 55
	s_cselect_b64 s[0:1], -1, 0
	v_writelane_b32 v245, s0, 56
	s_cmp_gt_u32 s87, 29
	s_nop 0
	v_writelane_b32 v245, s1, 57
	s_cselect_b64 s[0:1], -1, 0
	v_writelane_b32 v245, s0, 58
	s_nop 1
	v_writelane_b32 v245, s1, 59
	v_sub_co_u32_e64 v214, s[0:1], s2, 32
	s_xor_b64 s[0:1], s[0:1], -1
	s_nop 0
	v_writelane_b32 v245, s0, 60
	s_nop 1
	v_writelane_b32 v245, s1, 61
	s_sub_i32 s0, s94, 32
	v_writelane_b32 v245, s0, 62
	s_lshl_b32 s0, s3, 6
	s_addk_i32 s0, 0x2000
	v_writelane_b32 v245, s0, 63
	s_lshl_b32 s0, s3, 3
	s_cmpk_lt_i32 s2, 0x198
	v_writelane_b32 v244, s0, 0
	s_mul_hi_i32 s0, s2, 0x78787879
	s_cselect_b64 s[10:11], -1, 0
	v_writelane_b32 v244, s10, 1
	s_lshr_b32 s1, s0, 31
	s_ashr_i32 s0, s0, 6
	v_writelane_b32 v244, s11, 2
	s_add_i32 s10, s0, s1
	s_mul_i32 s0, s10, 0x88
	s_sub_i32 s0, s2, s0
	s_bfe_u32 s1, s0, 0x3001c
	s_add_i32 s1, s0, s1
	s_and_b32 s3, s1, 0xfff8
	s_sub_i32 s9, s0, s3
	s_sext_i32_i16 s0, s1
	s_ashr_i32 s11, s10, 31
	s_ashr_i32 s14, s0, 3
	s_lshl_b64 s[0:1], s[10:11], 11
	v_writelane_b32 v244, s0, 3
	s_nop 1
	v_writelane_b32 v244, s1, 4
	s_mov_b32 s0, s10
	v_writelane_b32 v244, s0, 5
	s_nop 1
	v_writelane_b32 v244, s1, 6
	s_lshl_b64 s[0:1], s[10:11], 21
	v_writelane_b32 v244, s0, 7
	s_cmpk_lt_i32 s2, 0x88
	s_nop 0
	v_writelane_b32 v244, s1, 8
	s_cselect_b64 s[0:1], -1, 0
	v_writelane_b32 v244, s0, 9
	s_cmpk_gt_u32 s2, 0x87
	s_nop 0
	v_writelane_b32 v244, s1, 10
	s_cselect_b64 s[0:1], -1, 0
	v_writelane_b32 v244, s0, 11
	s_nop 1
	v_writelane_b32 v244, s1, 12
	s_add_i32 s0, s84, 0xfffffbc0
	v_writelane_b32 v244, s0, 13
	s_add_i32 s0, s88, 0xfffffbc0
	s_cmpk_lt_i32 s2, 0x200
	v_writelane_b32 v244, s0, 14
	s_cselect_b64 s[0:1], -1, 0
	v_writelane_b32 v244, s0, 15
	s_ashr_i32 s3, s2, 31
	s_and_b32 s12, s2, 15
	v_writelane_b32 v244, s1, 16
	s_lshr_b32 s0, s3, 23
	s_add_i32 s0, s2, s0
	s_and_b32 s0, s0, 0xfe00
	s_sub_i32 s0, s2, s0
	s_sext_i32_i16 s1, s0
	s_bfe_u32 s1, s1, 0x3001c
	s_add_i32 s1, s0, s1
	s_and_b32 s4, s1, 0xfff8
	s_sub_i32 s15, s0, s4
	s_sext_i32_i16 s0, s1
	s_ashr_i32 s16, s0, 3
	v_readfirstlane_b32 s0, v0
	s_ashr_i32 s4, s0, 4
	s_add_i32 s10, s4, 32
	s_lshl_b32 s0, s4, 5
	s_ashr_i32 s11, s10, 31
	s_lshl_b32 s13, s12, 19
	s_ashr_i32 s1, s0, 31
	s_lshl_b32 s17, s15, 6
	v_writelane_b32 v244, s13, 17
	s_lshl_b64 s[18:19], s[10:11], 19
	v_writelane_b32 v244, s18, 18
	s_cmp_gt_i32 s4, -1
	s_nop 0
	v_writelane_b32 v244, s19, 19
	s_cselect_b64 s[18:19], -1, 0
	v_writelane_b32 v244, s18, 20
	s_ashr_i32 s11, s10, 3
	s_lshl_b32 s13, s10, 8
	v_writelane_b32 v244, s19, 21
	v_writelane_b32 v244, s11, 22
	s_lshl_b32 s10, s12, 8
	v_writelane_b32 v244, s10, 23
	s_and_b32 s56, s2, 7
	s_lshr_b32 s57, s2, 3
	s_sub_i32 s57, s57, 8
	s_lshr_b32 s58, s57, 1
	s_lshl_b32 s58, s58, 4
	s_lshl_b32 s56, s56, 1
	s_add_i32 s58, s58, s56
	s_and_b32 s57, s57, 1
	s_add_i32 s58, s58, s57
	s_add_i32 s58, s58, 64
	s_sub_i32 s57, s2, 64
	s_cmpk_lt_u32 s57, 0xa0
	s_cselect_b32 s54, s58, s2
	s_sub_i32 s56, s2, 0xe0
	s_and_b32 s57, s56, 1
	s_lshl_b32 s57, s57, 1
	s_bfe_u32 s58, s56, 0x10003
	s_add_i32 s57, s57, s58
	s_lshl_b32 s57, s57, 2
	s_bfe_u32 s58, s56, 0x20001
	s_add_i32 s57, s57, s58
	s_and_b32 s58, s56, 16
	s_add_i32 s57, s57, s58
	s_add_i32 s57, s57, 0xe0
	s_cmpk_gt_u32 s2, 0xdf
	s_cselect_b32 s54, s57, s54
	s_mov_b32 s55, 0
	s_lshl_b32 s10, s54, 4
	s_add_i32 s11, s10, 0x1200
	s_mul_i32 s10, s54, 36
	s_add_i32 s18, s10, 0x80
	s_or_b32 s10, s13, 0x80
	v_writelane_b32 v244, s10, 24
	s_or_b32 s10, s13, 0x90
	v_writelane_b32 v244, s10, 25
	s_or_b32 s10, s13, 0xa0
	v_writelane_b32 v244, s10, 26
	v_writelane_b32 v244, s13, 27
	s_or_b32 s10, s13, 0xb0
	v_writelane_b32 v244, s10, 28
	s_add_i32 s10, s54, 1
	s_cmpk_lt_u32 s10, 0xe0
	s_cselect_b32 s12, 36, 16
	s_cmp_gt_i32 s54, 62
	s_cselect_b32 s19, s12, 38
	s_add_i32 s12, s54, 2
	s_cmpk_lt_u32 s12, 0xe0
	s_cselect_b32 s12, 36, 16
	s_cmp_gt_i32 s54, 61
	s_cselect_b32 s12, s12, 38
	s_add_i32 s20, s19, s12
	s_cmpk_gt_u32 s2, 0xdf
	s_cselect_b64 s[12:13], -1, 0
	v_writelane_b32 v244, s12, 29
	s_nop 1
	v_writelane_b32 v244, s13, 30
	s_and_b64 s[12:13], s[12:13], exec
	s_cselect_b32 s21, 16, 36
	s_cselect_b32 s22, s11, s18
	s_and_b64 s[12:13], vcc, exec
	s_cselect_b32 s11, s18, s11
	s_cmp_lt_i32 s54, 64
	s_mul_i32 s12, s54, 38
	s_cselect_b32 s13, s12, s22
	s_cselect_b32 s18, s12, s11
	s_cselect_b32 s21, 38, s21
	s_and_b32 s12, s13, 62
	s_ashr_i32 s11, s13, 6
	s_sub_i32 s12, 64, s12
	s_cmp_lt_u32 s12, s21
	v_mov_b32_e32 v0, s12
	s_cselect_b64 s[12:13], -1, 0
	v_sub_u32_e64 v0, s21, v0 clamp
	v_writelane_b32 v244, s12, 31
	s_add_i32 s11, s11, 1
	v_writelane_b32 v244, s13, 32
	s_lshr_b32 s92, s11, 2
	s_and_b32 s28, s11, 3
	s_sub_i32 s60, s11, 38
	s_mul_i32 s61, s60, 57
	s_lshr_b32 s61, s61, 9
	s_mul_i32 s62, s61, 9
	s_sub_i32 s62, s60, s62
	s_mul_i32 s62, s62, 3
	s_lshr_b32 s63, s61, 2
	s_add_i32 s62, s62, s63
	s_and_b32 s63, s61, 3
	s_cmpk_lt_u32 s11, 0x80
	s_cselect_b32 s92, s62, s92
	s_cselect_b32 s28, s63, s28
	s_sub_i32 s60, s11, 19
	s_cmpk_lt_u32 s11, 19
	s_cselect_b32 s60, s11, s60
	s_cselect_b32 s61, 0, 1
	s_mul_i32 s62, s60, 3
	s_add_i32 s62, s62, 2
	s_add_i32 s63, s61, 2
	s_sub_i32 s64, s60, 9
	s_lshr_b32 s65, s64, 1
	s_add_i32 s65, s65, 27
	s_and_b32 s64, s64, 1
	s_lshl_b32 s64, s64, 1
	s_add_i32 s64, s64, s61
	s_cmpk_lt_u32 s60, 9
	s_cselect_b32 s62, s62, s65
	s_cselect_b32 s63, s63, s64
	s_cmpk_lt_u32 s11, 38
	s_cselect_b32 s92, s62, s92
	s_cselect_b32 s28, s63, s28
	v_readfirstlane_b32 s11, v0
	s_nop 1
	v_writelane_b32 v244, s11, 33
	s_sub_i32 s11, 64, s11
	s_cmp_gt_u32 s11, s19
	s_cselect_b32 s22, 2, 1
	s_cmp_gt_u32 s11, s20
	s_cselect_b64 s[12:13], -1, 0
	s_cmp_lg_u64 s[12:13], 0
	s_addc_u32 s11, s22, 0
	v_writelane_b32 v244, s11, 34
	s_ashr_i32 s11, s10, 31
	s_lshl_b64 s[10:11], s[10:11], 17
	v_writelane_b32 v244, s10, 35
	s_lshl_b64 s[12:13], s[54:55], 17
	s_nop 0
	v_writelane_b32 v244, s11, 36
	s_sext_i32_i16 s10, s8
	s_cmp_lt_i32 s10, 0
	s_cselect_b32 s10, s93, 0x66
	s_mul_i32 s8, s10, s8
	s_add_i32 s8, s8, s6
	s_sext_i32_i16 s6, s8
	s_mulk_i32 s6, 0x2aab
	s_lshr_b32 s10, s6, 31
	s_ashr_i32 s6, s6, 21
	s_add_i32 s6, s6, s10
	s_mul_i32 s10, s6, 0xc0
	s_sext_i32_i16 s6, s6
	s_lshl_b32 s11, s6, 3
	v_writelane_b32 v244, s12, 37
	s_sub_i32 s6, 34, s11
	s_sub_i32 s10, s8, s10
	v_writelane_b32 v244, s13, 38
	s_min_u32 s12, s6, 8
	s_sext_i32_i16 s6, s7
	s_cmp_lt_i32 s6, 0
	s_cselect_b32 s6, 52, 51
	s_mul_i32 s6, s6, s7
	s_add_i32 s6, s6, s5
	s_sext_i32_i16 s5, s6
	s_mulk_i32 s5, 0x2aab
	s_lshr_b32 s7, s5, 31
	s_ashr_i32 s5, s5, 20
	s_add_i32 s5, s5, s7
	s_mul_i32 s7, s5, 0x60
	s_sext_i32_i16 s5, s5
	s_lshl_b32 s5, s5, 3
	s_sub_i32 s13, s6, s7
	s_sub_i32 s6, 34, s5
	s_min_u32 s22, s6, 8
	s_sext_i32_i16 s6, s9
	s_cmp_lt_i32 s6, 0
	s_cselect_b32 s6, 18, 17
	s_mul_i32 s6, s6, s9
	s_add_i32 s6, s6, s14
	s_sext_i32_i16 s7, s6
	s_bfe_u32 s7, s7, 0x5001a
	s_add_i32 s7, s6, s7
	s_and_b32 s8, s7, 0xffe0
	s_sub_i32 s14, s6, s8
	s_sext_i32_i16 s6, s7
	s_ashr_i32 s6, s6, 5
	s_lshl_b32 s23, s6, 3
	s_sub_i32 s6, 34, s23
	s_min_u32 s24, s6, 8
	s_sext_i32_i16 s6, s15
	s_cmp_lt_i32 s6, 0
	s_mulk_i32 s15, 0x41
	s_cselect_b32 s6, s15, s17
	s_add_i32 s6, s6, s16
	s_sext_i32_i16 s7, s6
	s_bfe_u32 s7, s7, 0x70018
	s_add_i32 s7, s6, s7
	s_and_b32 s8, s7, 0xff80
	s_sub_i32 s6, s6, s8
	s_bfe_i32 s8, s6, 0x80000
	s_bfe_u32 s8, s8, 0x3000c
	s_add_i32 s8, s6, s8
	s_and_b32 s9, s8, 0xf8
	s_sext_i32_i16 s7, s7
	s_sub_i32 s6, s6, s9
	s_and_b32 s15, s18, 62
	s_ashr_i32 s7, s7, 7
	s_bfe_i32 s8, s8, 0x80000
	s_sub_i32 s9, 64, s15
	s_lshl_b32 s7, s7, 3
	s_sext_i32_i16 s8, s8
	s_sext_i32_i8 s6, s6
	s_min_u32 s9, s9, s21
	s_add_i32 s30, s7, s6
	s_ashr_i32 s6, s8, 3
	v_writelane_b32 v244, s6, 39
	s_lshr_b32 s6, s8, 3
	s_lshr_b32 s56, s18, 6
	s_lshr_b32 s18, s56, 2
	s_and_b32 s17, s56, 3
	s_sub_i32 s60, s56, 38
	s_mul_i32 s61, s60, 57
	s_lshr_b32 s61, s61, 9
	s_mul_i32 s62, s61, 9
	s_sub_i32 s62, s60, s62
	s_mul_i32 s62, s62, 3
	s_lshr_b32 s63, s61, 2
	s_add_i32 s62, s62, s63
	s_and_b32 s63, s61, 3
	s_cmpk_lt_u32 s56, 0x80
	s_cselect_b32 s18, s62, s18
	s_cselect_b32 s17, s63, s17
	s_sub_i32 s60, s56, 19
	s_cmpk_lt_u32 s56, 19
	s_cselect_b32 s60, s56, s60
	s_cselect_b32 s61, 0, 1
	s_mul_i32 s62, s60, 3
	s_add_i32 s62, s62, 2
	s_add_i32 s63, s61, 2
	s_sub_i32 s64, s60, 9
	s_lshr_b32 s65, s64, 1
	s_add_i32 s65, s65, 27
	s_and_b32 s64, s64, 1
	s_lshl_b32 s64, s64, 1
	s_add_i32 s64, s64, s61
	s_cmpk_lt_u32 s60, 9
	s_cselect_b32 s62, s62, s65
	s_cselect_b32 s63, s63, s64
	s_cmpk_lt_u32 s56, 38
	s_cselect_b32 s18, s62, s18
	s_cselect_b32 s17, s63, s17
	s_sub_i32 s7, 64, s9
	s_cmp_gt_u32 s7, s19
	s_cselect_b32 s16, 2, 1
	s_cmp_gt_u32 s7, s20
	v_writelane_b32 v244, s9, 40
	s_cselect_b64 s[8:9], -1, 0
	s_cmp_lg_u64 s[8:9], 0
	s_addc_u32 s8, s16, 0
	s_bfe_i64 s[6:7], s[6:7], 0x100000
	s_lshl_b64 s[6:7], s[6:7], 19
	v_writelane_b32 v244, s6, 41
	s_ashr_i32 s19, s18, 31
	s_ashr_i32 s31, s30, 31
	v_writelane_b32 v244, s7, 42
	s_lshl_b32 s6, s15, 7
	v_writelane_b32 v244, s6, 43
	v_writelane_b32 v244, s17, 44
	s_lshl_b32 s6, s17, 21
	v_writelane_b32 v244, s6, 45
	s_mov_b32 s6, s18
	v_writelane_b32 v244, s6, 46
	v_cvt_f32_ubyte0_e32 v1, s12
	v_rcp_iflag_f32_e32 v2, v1
	v_writelane_b32 v244, s7, 47
	s_lshl_b64 s[6:7], s[18:19], 21
	v_writelane_b32 v244, s6, 48
	s_nop 1
	v_writelane_b32 v244, s7, 49
	s_mov_b32 s6, s30
	v_writelane_b32 v244, s6, 50
	s_nop 1
	v_writelane_b32 v244, s7, 51
	s_lshl_b64 s[6:7], s[30:31], 19
	v_writelane_b32 v244, s6, 52
	s_cmp_eq_u32 s15, 0
	s_nop 0
	v_writelane_b32 v244, s7, 53
	s_cselect_b32 s6, s8, 0
	v_writelane_b32 v244, s6, 54
	s_sext_i32_i16 s6, s10
	v_cvt_f32_i32_e32 v0, s6
	s_cselect_b32 s7, 2, 1
	s_ashr_i32 s6, s6, 30
	v_writelane_b32 v244, s7, 55
	v_mul_f32_e32 v2, v0, v2
	v_trunc_f32_e32 v2, v2
	v_fma_f32 v0, -v2, v1, v0
	s_or_b32 s8, s6, 1
	v_cmp_ge_f32_e64 s[6:7], |v0|, v1
	v_cvt_i32_f32_e32 v0, v2
	s_and_b64 s[6:7], s[6:7], exec
	s_cselect_b32 s6, s8, 0
	v_cvt_f32_ubyte0_e32 v1, s22
	v_readfirstlane_b32 s7, v0
	s_add_i32 s15, s7, s6
	s_mul_i32 s6, s15, s12
	s_sub_i32 s6, s10, s6
	s_sext_i32_i16 s6, s6
	s_add_i32 s6, s11, s6
	v_writelane_b32 v244, s6, 56
	s_sext_i32_i16 s6, s13
	v_cvt_f32_i32_e32 v0, s6
	v_rcp_iflag_f32_e32 v2, v1
	s_ashr_i32 s6, s6, 30
	s_or_b32 s8, s6, 1
	v_mul_f32_e32 v2, v0, v2
	v_trunc_f32_e32 v2, v2
	v_fma_f32 v0, -v2, v1, v0
	v_cmp_ge_f32_e64 s[6:7], |v0|, v1
	v_cvt_i32_f32_e32 v0, v2
	s_and_b64 s[6:7], s[6:7], exec
	s_cselect_b32 s6, s8, 0
	v_cvt_f32_ubyte0_e32 v1, s24
	v_readfirstlane_b32 s7, v0
	s_add_i32 s6, s7, s6
	s_mul_i32 s7, s6, s22
	s_sub_i32 s7, s13, s7
	s_sext_i32_i8 s7, s7
	s_add_i32 s10, s5, s7
	s_sext_i32_i16 s5, s14
	v_cvt_f32_i32_e32 v0, s5
	v_rcp_iflag_f32_e32 v2, v1
	s_bfe_i64 s[8:9], s[6:7], 0x80000
	s_lshl_b64 s[8:9], s[8:9], 18
	v_writelane_b32 v244, s8, 57
	s_ashr_i32 s11, s10, 31
	v_mul_f32_e32 v2, v0, v2
	v_writelane_b32 v244, s9, 58
	s_mov_b32 s8, s10
	v_writelane_b32 v244, s8, 59
	v_trunc_f32_e32 v2, v2
	v_fma_f32 v0, -v2, v1, v0
	v_writelane_b32 v244, s9, 60
	s_lshl_b64 s[8:9], s[10:11], 18
	v_writelane_b32 v244, s8, 61
	s_ashr_i32 s5, s5, 30
	s_or_b32 s5, s5, 1
	v_writelane_b32 v244, s9, 62
	v_cmp_ge_f32_e64 s[8:9], |v0|, v1
	v_cvt_i32_f32_e32 v0, v2
	s_and_b64 s[8:9], s[8:9], exec
	v_writelane_b32 v244, s26, 63
	s_sext_i32_i8 s6, s6
	s_cselect_b32 s5, s5, 0
	v_writelane_b32 v243, s27, 0
	v_writelane_b32 v243, s6, 1
	v_readfirstlane_b32 s6, v0
	s_add_i32 s6, s6, s5
	s_mul_i32 s5, s6, s24
	s_sub_i32 s5, s14, s5
	s_sext_i32_i8 s5, s5
	s_add_i32 s5, s23, s5
	s_mul_i32 s7, s95, s94
	v_writelane_b32 v243, s5, 2
	s_sext_i32_i16 s5, s15
	s_mul_i32 s95, s7, s33
	v_writelane_b32 v243, s5, 3
	s_sext_i32_i8 s5, s6
	s_bfe_i64 s[6:7], s[6:7], 0x80000
	v_writelane_b32 v243, s5, 4
	s_lshl_b64 s[6:7], s[6:7], 19
	v_writelane_b32 v243, s6, 5
	s_ashr_i32 s5, s4, 31
	s_lshl_b64 s[4:5], s[4:5], 19
	v_writelane_b32 v243, s7, 6
	v_writelane_b32 v243, s4, 7
	s_lshl_b64 s[0:1], s[0:1], 2
	s_ashr_i32 s85, s84, 31
	v_writelane_b32 v243, s5, 8
	v_writelane_b32 v243, s0, 9
	s_lshl_b32 s4, s94, 5
	v_mbcnt_lo_u32_b32 v0, -1, 0
	v_writelane_b32 v243, s1, 10
	v_writelane_b32 v243, s84, 11
	s_add_i32 s1, s84, 0xfffff800
	s_movk_i32 s0, 0x110
	v_writelane_b32 v243, s85, 12
	v_writelane_b32 v243, s1, 13
	s_lshl_b32 s1, s2, 5
	v_writelane_b32 v243, s1, 14
	s_addk_i32 s1, 0xdc00
	v_writelane_b32 v243, s1, 15
	v_writelane_b32 v243, s4, 16
	s_add_i32 s1, s4, 0xfffffc00
	v_writelane_b32 v243, s1, 17
	s_lshl_b32 s1, s94, 10
	v_writelane_b32 v243, s1, 18
	s_lshl_b32 s1, s2, 12
	v_writelane_b32 v243, s1, 19
	s_lshl_b32 s1, s94, 14
	v_writelane_b32 v243, s1, 20
	s_add_i32 s1, 0, 0x20000
	v_writelane_b32 v243, s1, 21
	s_add_i32 s1, 0, 0x20004
	v_writelane_b32 v243, s1, 22
	v_cmp_gt_i32_e64 s[0:1], s0, v214
	v_cndmask_b32_e64 v215, 0, 1, s[26:27]
	v_mbcnt_hi_u32_b32 v221, -1, v0
	v_writelane_b32 v243, s0, 23
	s_movk_i32 s33, 0x2000
	s_mov_b32 s84, s28
	v_writelane_b32 v243, s1, 24
	v_cmp_gt_u32_e64 s[0:1], 64, v195
	s_mov_b64 s[4:5], 0x80
	s_nop 0
	v_writelane_b32 v243, s0, 25
	s_nop 1
	v_writelane_b32 v243, s1, 26
	s_lshl_b64 s[0:1], s[54:55], 2
	v_writelane_b32 v243, s0, 27
	s_nop 1
	v_writelane_b32 v243, s1, 28
	v_writelane_b32 v243, s36, 29
	s_nop 1
	v_writelane_b32 v243, s37, 30
	v_writelane_b32 v243, s38, 31
	s_nop 1
	v_writelane_b32 v243, s39, 32
	v_writelane_b32 v243, s40, 33
	s_nop 1
	v_writelane_b32 v243, s41, 34
	v_writelane_b32 v243, s42, 35
	s_nop 1
	v_writelane_b32 v243, s43, 36
	v_writelane_b32 v243, s44, 37
	s_nop 1
	v_writelane_b32 v243, s45, 38
	v_writelane_b32 v243, s46, 39
	s_nop 1
	v_writelane_b32 v243, s47, 40
	v_writelane_b32 v243, s48, 41
	s_nop 1
	v_writelane_b32 v243, s49, 42
	v_writelane_b32 v243, s94, 43
	s_nop 1
	v_writelane_b32 v243, s95, 44
	v_writelane_b32 v243, s82, 45
	s_nop 1
	v_writelane_b32 v243, s83, 46
	v_writelane_b32 v243, s86, 47
	v_writelane_b32 v243, s80, 48
	v_writelane_b32 v243, s81, 49
	v_writelane_b32 v243, s87, 50
	v_writelane_b32 v243, s89, 51
	v_writelane_b32 v243, s95, 52
	s_branch .LBB0_414
